# phase-1 copier stop threshold 708
# speedup vs baseline: 1.0039x; 1.0039x over previous
.Lcp1_entry:
	v_readfirstlane_b32 s0, v192
	v_lshlrev_b32_e32 v16, 4, v192
	s_add_u32 s4, s38, 0xc7b7100
	s_addc_u32 s5, s39, 0
	s_add_u32 s6, s38, 0xc7b7200
	s_addc_u32 s7, s39, 0
	s_lshr_b32 s0, s0, 6
	s_mov_b32 s1, 0
	s_mov_b32 s30, 2
	v_mov_b32_e32 v93, 0
	v_mov_b32_e32 v94, 1
	v_mov_b32_e32 v95, 16
	v_mov_b32_e32 v96, 20
	v_add_u32_e32 v17, 0x2000, v16
	v_add_u32_e32 v18, 0x4000, v16
	v_add_u32_e32 v19, 0x6000, v16
	v_add_u32_e32 v20, 0x8000, v16
	v_add_u32_e32 v21, 0xa000, v16
	v_add_u32_e32 v22, 0xc000, v16
	v_add_u32_e32 v23, 0xe000, v16
	v_add_u32_e32 v104, 0x10000, v16
	v_add_u32_e32 v105, 0x12000, v16
	v_add_u32_e32 v106, 0x14000, v16
	v_add_u32_e32 v107, 0x16000, v16
	v_add_u32_e32 v108, 0x18000, v16
	v_add_u32_e32 v109, 0x1a000, v16
	v_add_u32_e32 v110, 0x1c000, v16
	v_add_u32_e32 v111, 0x1e000, v16
	s_barrier
	s_cmp_lg_u32 s0, 0
	s_cbranch_scc1 .Lcp1_p0
	s_mov_b64 s[22:23], exec
	s_mov_b64 exec, 1
	global_load_dword v118, v93, s[6:7] sc1
	v_mov_b32_e32 v117, 0xa80
	s_waitcnt vmcnt(0)
	v_readfirstlane_b32 s25, v118
	s_cmpk_gt_u32 s25, 0x2c4
	s_cbranch_scc1 .Lcp1_pnone
	v_mov_b32_e32 v117, 2
	global_atomic_add v117, v93, v117, s[4:5] sc0
	s_waitcnt vmcnt(0)

.Lcp1_ac_A_j:
	s_lshl_b32 s18, s18, 17
	v_add_u32_e32 v92, s24, v16
	s_add_u32 s14, s36, s19
	s_addc_u32 s15, s37, 0
	s_add_u32 s14, s14, s18
	s_addc_u32 s15, s15, 0
	s_add_u32 s12, s12, s18
	s_addc_u32 s13, s13, 0
	s_add_u32 s12, s12, 0x2000
	s_addc_u32 s13, s13, 0
	global_load_dwordx4 v[180:183], v16, s[12:13] nt
	global_load_dwordx4 v[184:187], v17, s[12:13] nt
	global_load_dwordx4 v[188:191], v18, s[12:13] nt
	global_load_dwordx4 v[196:199], v19, s[12:13] nt
	global_load_dwordx4 v[200:203], v20, s[12:13] nt
	global_load_dwordx4 v[204:207], v21, s[12:13] nt
	global_load_dwordx4 v[208:211], v22, s[12:13] nt
	global_load_dwordx4 v[212:215], v23, s[12:13] nt
	global_load_dwordx4 v[216:219], v104, s[12:13] nt
	global_load_dwordx4 v[220:223], v105, s[12:13] nt
	global_load_dwordx4 v[224:227], v106, s[12:13] nt
	global_load_dwordx4 v[228:231], v107, s[12:13] nt
	global_load_dwordx4 v[244:247], v108, s[12:13] nt
	global_load_dwordx4 v[248:251], v109, s[12:13] nt
	global_load_dwordx4 v[4:7], v110, s[12:13] nt
	global_load_dwordx4 v[8:11], v92, s[12:13] nt
	s_waitcnt vmcnt(31)
	global_store_dwordx4 v16, v[30:33], s[10:11] nt
	s_waitcnt vmcnt(31)
	global_store_dwordx4 v17, v[34:37], s[10:11] nt
	s_waitcnt vmcnt(31)
	global_store_dwordx4 v18, v[38:41], s[10:11] nt
	s_waitcnt vmcnt(31)
	global_store_dwordx4 v19, v[42:45], s[10:11] nt
	s_waitcnt vmcnt(31)
	global_store_dwordx4 v20, v[46:49], s[10:11] nt
	s_waitcnt vmcnt(31)
	global_store_dwordx4 v21, v[50:53], s[10:11] nt
	s_waitcnt vmcnt(31)
	global_store_dwordx4 v22, v[54:57], s[10:11] nt
	s_waitcnt vmcnt(31)
	global_store_dwordx4 v23, v[58:61], s[10:11] nt
	s_waitcnt vmcnt(31)
	global_store_dwordx4 v104, v[62:65], s[10:11] nt
	s_waitcnt vmcnt(31)
	global_store_dwordx4 v105, v[66:69], s[10:11] nt
	s_waitcnt vmcnt(31)
	global_store_dwordx4 v106, v[70:73], s[10:11] nt
	s_waitcnt vmcnt(31)
	global_store_dwordx4 v107, v[74:77], s[10:11] nt
	s_waitcnt vmcnt(31)
	global_store_dwordx4 v108, v[164:167], s[10:11] nt
	s_waitcnt vmcnt(31)
	global_store_dwordx4 v109, v[168:171], s[10:11] nt
	s_waitcnt vmcnt(31)
	global_store_dwordx4 v110, v[172:175], s[10:11] nt
	s_waitcnt vmcnt(31)
	global_store_dwordx4 v91, v[176:179], s[10:11] nt
	s_cmp_lg_u32 s0, 0
	s_cbranch_scc1 .Lcp1_A_s4
	s_mov_b64 s[22:23], exec
	s_mov_b64 exec, 1
	s_cmp_lg_u32 s1, 0
	s_cbranch_scc1 .Lcp1_A_s4stop
	s_waitcnt vmcnt(32)
	v_readfirstlane_b32 s25, v118
	s_cmpk_gt_u32 s25, 0x2c4
	s_cselect_b32 s1, 1, 0
	v_readfirstlane_b32 s26, v117
	s_cmpk_ge_u32 s26, 0xa80
	s_cselect_b32 s27, 1, 0
	s_or_b32 s1, s1, s27
	s_branch .Lcp1_A_s4pub

.Lcp1_ac_B_j:
	s_lshl_b32 s18, s18, 17
	v_add_u32_e32 v91, s24, v16
	s_add_u32 s10, s36, s19
	s_addc_u32 s11, s37, 0
	s_add_u32 s10, s10, s18
	s_addc_u32 s11, s11, 0
	s_add_u32 s8, s8, s18
	s_addc_u32 s9, s9, 0
	s_add_u32 s8, s8, 0x2000
	s_addc_u32 s9, s9, 0
	global_load_dwordx4 v[30:33], v16, s[8:9] nt
	global_load_dwordx4 v[34:37], v17, s[8:9] nt
	global_load_dwordx4 v[38:41], v18, s[8:9] nt
	global_load_dwordx4 v[42:45], v19, s[8:9] nt
	global_load_dwordx4 v[46:49], v20, s[8:9] nt
	global_load_dwordx4 v[50:53], v21, s[8:9] nt
	global_load_dwordx4 v[54:57], v22, s[8:9] nt
	global_load_dwordx4 v[58:61], v23, s[8:9] nt
	global_load_dwordx4 v[62:65], v104, s[8:9] nt
	global_load_dwordx4 v[66:69], v105, s[8:9] nt
	global_load_dwordx4 v[70:73], v106, s[8:9] nt
	global_load_dwordx4 v[74:77], v107, s[8:9] nt
	global_load_dwordx4 v[164:167], v108, s[8:9] nt
	global_load_dwordx4 v[168:171], v109, s[8:9] nt
	global_load_dwordx4 v[172:175], v110, s[8:9] nt
	global_load_dwordx4 v[176:179], v91, s[8:9] nt
	s_waitcnt vmcnt(31)
	global_store_dwordx4 v16, v[180:183], s[14:15] nt
	s_waitcnt vmcnt(31)
	global_store_dwordx4 v17, v[184:187], s[14:15] nt
	s_waitcnt vmcnt(31)
	global_store_dwordx4 v18, v[188:191], s[14:15] nt
	s_waitcnt vmcnt(31)
	global_store_dwordx4 v19, v[196:199], s[14:15] nt
	s_waitcnt vmcnt(31)
	global_store_dwordx4 v20, v[200:203], s[14:15] nt
	s_waitcnt vmcnt(31)
	global_store_dwordx4 v21, v[204:207], s[14:15] nt
	s_waitcnt vmcnt(31)
	global_store_dwordx4 v22, v[208:211], s[14:15] nt
	s_waitcnt vmcnt(31)
	global_store_dwordx4 v23, v[212:215], s[14:15] nt
	s_waitcnt vmcnt(31)
	global_store_dwordx4 v104, v[216:219], s[14:15] nt
	s_waitcnt vmcnt(31)
	global_store_dwordx4 v105, v[220:223], s[14:15] nt
	s_waitcnt vmcnt(31)
	global_store_dwordx4 v106, v[224:227], s[14:15] nt
	s_waitcnt vmcnt(31)
	global_store_dwordx4 v107, v[228:231], s[14:15] nt
	s_waitcnt vmcnt(31)
	global_store_dwordx4 v108, v[244:247], s[14:15] nt
	s_waitcnt vmcnt(31)
	global_store_dwordx4 v109, v[248:251], s[14:15] nt
	s_waitcnt vmcnt(31)
	global_store_dwordx4 v110, v[4:7], s[14:15] nt
	s_waitcnt vmcnt(31)
	global_store_dwordx4 v92, v[8:11], s[14:15] nt
	s_cmp_lg_u32 s0, 0
	s_cbranch_scc1 .Lcp1_B_s4
	s_mov_b64 s[22:23], exec
	s_mov_b64 exec, 1
	s_cmp_lg_u32 s1, 0
	s_cbranch_scc1 .Lcp1_B_s4stop
	s_waitcnt vmcnt(32)
	v_readfirstlane_b32 s25, v118
	s_cmpk_gt_u32 s25, 0x2c4
	s_cselect_b32 s1, 1, 0
	v_readfirstlane_b32 s26, v117
	s_cmpk_ge_u32 s26, 0xa80
	s_cselect_b32 s27, 1, 0
	s_or_b32 s1, s1, s27
	s_branch .Lcp1_B_s4pub
